# seam prefetch extended: residual stream H touched at the seams before thin phases
# baseline (speedup 1.0000x reference)
.LBB0_610:
	s_waitcnt vmcnt(0)
	s_waitcnt vmcnt(0) lgkmcnt(0)
	s_barrier
	v_readlane_b32 s98, v250, 21
	s_nop 3
	s_cmp_eq_u32 s98, 0
	s_cbranch_scc1 .Lpf_skip_6
	s_mul_i32 s99, s33, 7
	s_add_i32 s99, s99, s98
	s_add_i32 s99, s99, -1
	s_mul_i32 s99, s99, 0xa000
	v_lshlrev_b32_e32 v251, 7, v178
	v_add_u32_e32 v251, s99, v251
	s_add_u32 s100, s88, 0x17d00000
	s_addc_u32 s101, s89, 0
	global_load_dword v252, v251, s[100:101]
	v_add_u32_e32 v251, 0x2000, v251
	global_load_dword v253, v251, s[100:101]
	v_add_u32_e32 v251, 0x2000, v251
	global_load_dword v254, v251, s[100:101]
	v_add_u32_e32 v251, 0x2000, v251
	global_load_dword v255, v251, s[100:101]
	v_add_u32_e32 v251, 0x2000, v251
	global_load_dword v252, v251, s[100:101]

.LBB0_908:
	s_cmp_lt_i32 s85, 10
	s_cbranch_scc1 .LBB0_962
	s_waitcnt vmcnt(0)
	s_waitcnt vmcnt(0) lgkmcnt(0)
	s_barrier
	v_readlane_b32 s98, v250, 21
	s_nop 3
	s_cmp_eq_u32 s98, 0
	s_cbranch_scc1 .Lpf_skip_9
	s_mul_i32 s99, s33, 7
	s_add_i32 s99, s99, s98
	s_add_i32 s99, s99, -1
	s_mul_i32 s99, s99, 0xa000
	v_lshlrev_b32_e32 v251, 7, v178
	v_add_u32_e32 v251, s99, v251
	s_add_u32 s100, s88, 0x17d00000
	s_addc_u32 s101, s89, 0
	global_load_dword v252, v251, s[100:101]
	v_add_u32_e32 v251, 0x2000, v251
	global_load_dword v253, v251, s[100:101]
	v_add_u32_e32 v251, 0x2000, v251
	global_load_dword v254, v251, s[100:101]
	v_add_u32_e32 v251, 0x2000, v251
	global_load_dword v255, v251, s[100:101]
	v_add_u32_e32 v251, 0x2000, v251
	global_load_dword v252, v251, s[100:101]

.LBB0_1414:
	s_cmp_lt_i32 s85, 13
	s_cbranch_scc1 .LBB0_1468
	s_waitcnt vmcnt(0)
	s_waitcnt vmcnt(0) lgkmcnt(0)
	s_barrier
	v_readlane_b32 s98, v250, 21
	s_nop 3
	s_cmp_eq_u32 s98, 0
	s_cbranch_scc1 .Lpf_skip_13
	s_mul_i32 s99, s33, 7
	s_add_i32 s99, s99, s98
	s_add_i32 s99, s99, -1
	s_mul_i32 s99, s99, 0x2000
	v_lshlrev_b32_e32 v251, 7, v178
	v_add_u32_e32 v251, s99, v251
	s_add_u32 s100, s88, 0x3900000
	s_addc_u32 s101, s89, 0
	global_load_dword v252, v251, s[100:101]

.LBB0_1776:
	s_cmp_lt_i32 s85, 18
	s_cbranch_scc1 .LBB0_1830
	s_waitcnt vmcnt(0)
	s_waitcnt vmcnt(0) lgkmcnt(0)
	s_barrier
	v_readlane_b32 s98, v250, 21
	s_nop 3
	s_cmp_eq_u32 s98, 0
	s_cbranch_scc1 .Lpf_skip_17
	s_mul_i32 s99, s33, 7
	s_add_i32 s99, s99, s98
	s_add_i32 s99, s99, -1
	s_mul_i32 s99, s99, 0xa000
	v_lshlrev_b32_e32 v251, 7, v178
	v_add_u32_e32 v251, s99, v251
	s_add_u32 s100, s88, 0x17d00000
	s_addc_u32 s101, s89, 0
	global_load_dword v252, v251, s[100:101]
	v_add_u32_e32 v251, 0x2000, v251
	global_load_dword v253, v251, s[100:101]
	v_add_u32_e32 v251, 0x2000, v251
	global_load_dword v254, v251, s[100:101]
	v_add_u32_e32 v251, 0x2000, v251
	global_load_dword v255, v251, s[100:101]
	v_add_u32_e32 v251, 0x2000, v251
	global_load_dword v252, v251, s[100:101]

.LBB0_2602:
	s_cmp_lt_i32 s85, 26
	s_cbranch_scc1 .LBB0_2656
	s_waitcnt vmcnt(0)
	s_waitcnt vmcnt(0) lgkmcnt(0)
	s_barrier
	v_readlane_b32 s98, v250, 21
	s_nop 3
	s_cmp_eq_u32 s98, 0
	s_cbranch_scc1 .Lpf_skip_25
	s_mul_i32 s99, s33, 7
	s_add_i32 s99, s99, s98
	s_add_i32 s99, s99, -1
	s_mul_i32 s99, s99, 0xa000
	v_lshlrev_b32_e32 v251, 7, v178
	v_add_u32_e32 v251, s99, v251
	s_add_u32 s100, s88, 0x17d00000
	s_addc_u32 s101, s89, 0
	global_load_dword v252, v251, s[100:101]
	v_add_u32_e32 v251, 0x2000, v251
	global_load_dword v253, v251, s[100:101]
	v_add_u32_e32 v251, 0x2000, v251
	global_load_dword v254, v251, s[100:101]
	v_add_u32_e32 v251, 0x2000, v251
	global_load_dword v255, v251, s[100:101]
	v_add_u32_e32 v251, 0x2000, v251
	global_load_dword v252, v251, s[100:101]

.LBB0_3067:
	s_cmp_lt_i32 s85, 30
	s_cbranch_scc1 .LBB0_3121
	s_waitcnt vmcnt(0)
	s_waitcnt vmcnt(0) lgkmcnt(0)
	s_barrier
	v_readlane_b32 s98, v250, 21
	s_nop 3
	s_cmp_eq_u32 s98, 0
	s_cbranch_scc1 .Lpf_skip_29
	s_mul_i32 s99, s33, 7
	s_add_i32 s99, s99, s98
	s_add_i32 s99, s99, -1
	s_mul_i32 s99, s99, 0xa000
	v_lshlrev_b32_e32 v251, 7, v178
	v_add_u32_e32 v251, s99, v251
	s_add_u32 s100, s88, 0x17d00000
	s_addc_u32 s101, s89, 0
	global_load_dword v252, v251, s[100:101]
	v_add_u32_e32 v251, 0x2000, v251
	global_load_dword v253, v251, s[100:101]
	v_add_u32_e32 v251, 0x2000, v251
	global_load_dword v254, v251, s[100:101]
	v_add_u32_e32 v251, 0x2000, v251
	global_load_dword v255, v251, s[100:101]
	v_add_u32_e32 v251, 0x2000, v251
	global_load_dword v252, v251, s[100:101]

.LBB0_3281:
	s_cmp_lt_i32 s85, 33
	s_cbranch_scc1 .LBB0_3335
	s_waitcnt vmcnt(0)
	s_waitcnt vmcnt(0) lgkmcnt(0)
	s_barrier
	v_readlane_b32 s98, v250, 21
	s_nop 3
	s_cmp_eq_u32 s98, 0
	s_cbranch_scc1 .Lpf_skip_32
	s_mul_i32 s99, s33, 7
	s_add_i32 s99, s99, s98
	s_add_i32 s99, s99, -1
	s_mul_i32 s99, s99, 0xa000
	v_lshlrev_b32_e32 v251, 7, v178
	v_add_u32_e32 v251, s99, v251
	s_add_u32 s100, s88, 0x17d00000
	s_addc_u32 s101, s89, 0
	global_load_dword v252, v251, s[100:101]
	v_add_u32_e32 v251, 0x2000, v251
	global_load_dword v253, v251, s[100:101]
	v_add_u32_e32 v251, 0x2000, v251
	global_load_dword v254, v251, s[100:101]
	v_add_u32_e32 v251, 0x2000, v251
	global_load_dword v255, v251, s[100:101]
	v_add_u32_e32 v251, 0x2000, v251
	global_load_dword v252, v251, s[100:101]
.Lpf_skip_32:
	s_mov_b64 s[0:1], exec
	v_readlane_b32 s2, v250, 19
	v_readlane_b32 s3, v250, 20
	s_and_b64 s[2:3], s[0:1], s[2:3]
	s_mov_b64 exec, s[2:3]
	s_cbranch_execz .LBB0_3334
	s_add_i32 s2, 0, 0x21020
	v_mov_b32_e32 v0, s2
	s_waitcnt vmcnt(0) expcnt(0) lgkmcnt(0)
	ds_read_b32 v2, v0
	s_add_i32 s2, 0, 0x21024
	v_mov_b32_e32 v0, s2
	ds_read_b32 v0, v0
	s_waitcnt lgkmcnt(1)
	v_cmp_ne_u32_e32 vcc, 0, v2
	s_cbranch_vccnz .LBB0_3298
	v_readlane_b32 s2, v250, 0
	v_readlane_b32 s3, v250, 1
	s_load_dwordx2 s[6:7], s[2:3], 0x4
	s_add_u32 s2, s86, 0x1000
	s_addc_u32 s3, s87, 0
	s_add_u32 s4, s86, 0x1100
	s_addc_u32 s5, s87, 0
	s_waitcnt lgkmcnt(0)
	s_mul_i32 s16, s6, s61
	s_add_u32 s6, s86, 0x1200
	s_mul_i32 s16, s16, s7
	s_addc_u32 s7, s87, 0
	s_add_u32 s8, s86, 0x1300
	s_addc_u32 s9, s87, 0
	s_mov_b32 s17, 1
	v_mov_b32_e32 v16, 0
	s_branch .LBB0_3286
